# v25 + attention: per-head sink logit via scalar load issued at the start of the QK part (prompt) instead of vector load + s_waitcnt vmcnt(0) in the softmax
# speedup vs baseline: 1.0058x; 1.0058x over previous
.LBB0_1256:
	s_and_b32 s61, s59, 1
	s_mov_b64 s[56:57], -1
	s_and_b64 vcc, exec, s[6:7]
	s_cbranch_vccz .LBB0_1262
	s_andn2_b64 vcc, exec, s[68:69]
	s_cbranch_vccnz .LBB0_1261
	ds_read_b128 v[0:3], v199
	ds_read_b128 v[206:209], v199 offset:32
	ds_read_b128 v[210:213], v199 offset:64
	ds_read_b128 v[214:217], v199 offset:96
	ds_read_b128 v[4:7], v200 offset:33792
	ds_read_b128 v[8:11], v200 offset:33824
	s_lshl_b32 s6, s61, 2
	v_readlane_b32 s7, v253, 46
	s_or_b32 s54, s6, s7
	s_waitcnt lgkmcnt(1)
	v_mfma_f32_32x32x16_bf16 v[90:105], v[4:7], v[0:3], 0
	ds_read_b128 v[4:7], v200 offset:33856
	ds_read_b128 v[224:227], v200 offset:52256
	v_readlane_b32 s6, v253, 48
	v_readlane_b32 s7, v253, 49
	s_waitcnt lgkmcnt(2)
	v_mfma_f32_32x32x16_bf16 v[90:105], v[8:11], v[206:209], v[90:105]
	s_waitcnt lgkmcnt(1)
	v_mfma_f32_32x32x16_bf16 v[90:105], v[4:7], v[210:213], v[90:105]
	ds_read_b128 v[4:7], v200 offset:33888
	s_waitcnt lgkmcnt(0)
	v_mfma_f32_32x32x16_bf16 v[90:105], v[4:7], v[214:217], v[90:105]
	ds_read_b128 v[4:7], v200 offset:38400
	s_waitcnt lgkmcnt(0)
	v_mfma_f32_32x32x16_bf16 v[74:89], v[4:7], v[0:3], 0
	ds_read_b128 v[4:7], v200 offset:38432
	s_nop 7
	v_cndmask_b32_e64 v222, v235, v90, s[6:7]
	v_readlane_b32 s6, v253, 50
	v_readlane_b32 s7, v253, 51
	s_nop 1
	v_cndmask_b32_e64 v236, v235, v91, s[6:7]
	s_waitcnt lgkmcnt(0)
	v_mfma_f32_32x32x16_bf16 v[74:89], v[4:7], v[206:209], v[74:89]
	ds_read_b128 v[4:7], v200 offset:38464
	v_readlane_b32 s6, v253, 52
	v_readlane_b32 s7, v253, 53
	s_waitcnt lgkmcnt(0)
	v_mfma_f32_32x32x16_bf16 v[74:89], v[4:7], v[210:213], v[74:89]
	ds_read_b128 v[4:7], v200 offset:38496
	s_waitcnt lgkmcnt(0)
	v_mfma_f32_32x32x16_bf16 v[74:89], v[4:7], v[214:217], v[74:89]
	ds_read_b128 v[4:7], v200 offset:43008
	s_waitcnt lgkmcnt(0)
	v_mfma_f32_32x32x16_bf16 v[58:73], v[4:7], v[0:3], 0
	ds_read_b128 v[4:7], v200 offset:43040
	s_waitcnt lgkmcnt(0)
	v_mfma_f32_32x32x16_bf16 v[58:73], v[4:7], v[206:209], v[58:73]
	ds_read_b128 v[4:7], v200 offset:43072
	s_waitcnt lgkmcnt(0)
	v_mfma_f32_32x32x16_bf16 v[58:73], v[4:7], v[210:213], v[58:73]
	ds_read_b128 v[4:7], v200 offset:43104
	s_waitcnt lgkmcnt(0)
	v_mfma_f32_32x32x16_bf16 v[58:73], v[4:7], v[214:217], v[58:73]
	ds_read_b128 v[4:7], v200 offset:47616
	s_waitcnt lgkmcnt(0)
	v_mfma_f32_32x32x16_bf16 v[42:57], v[4:7], v[0:3], 0
	ds_read_b128 v[4:7], v200 offset:47648
	s_waitcnt lgkmcnt(0)
	v_mfma_f32_32x32x16_bf16 v[42:57], v[4:7], v[206:209], v[42:57]
	ds_read_b128 v[4:7], v200 offset:47680
	s_waitcnt lgkmcnt(0)
	v_mfma_f32_32x32x16_bf16 v[42:57], v[4:7], v[210:213], v[42:57]
	ds_read_b128 v[4:7], v200 offset:47712
	s_waitcnt lgkmcnt(0)
	v_mfma_f32_32x32x16_bf16 v[42:57], v[4:7], v[214:217], v[42:57]
	ds_read_b128 v[4:7], v200 offset:52224
	s_waitcnt lgkmcnt(0)
	v_mfma_f32_32x32x16_bf16 v[0:15], v[4:7], v[0:3], 0
	v_mfma_f32_32x32x16_bf16 v[0:15], v[224:227], v[206:209], v[0:15]
	ds_read_b128 v[206:209], v200 offset:52288
	s_waitcnt lgkmcnt(0)
	v_mfma_f32_32x32x16_bf16 v[0:15], v[206:209], v[210:213], v[0:15]
	ds_read_b128 v[206:209], v200 offset:52320
	s_waitcnt lgkmcnt(0)
	v_mfma_f32_32x32x16_bf16 v[0:15], v[206:209], v[214:217], v[0:15]
	v_cndmask_b32_e64 v217, v235, v92, s[6:7]
	v_readlane_b32 s6, v253, 54
	v_readlane_b32 s7, v253, 55
	s_nop 8
	v_max_f32_e32 v4, v222, v222
	v_max_f32_e32 v4, 0xff800000, v4
	v_cndmask_b32_e64 v216, v93, v235, s[6:7]
	v_readlane_b32 s6, v253, 56
	v_readlane_b32 s7, v253, 57
	v_max3_f32 v4, v4, v236, v217
	s_nop 0
	v_cndmask_b32_e64 v215, v94, v235, s[6:7]
	v_readlane_b32 s6, v253, 58
	v_readlane_b32 s7, v253, 59
	v_max3_f32 v4, v4, v216, v215
	s_nop 0
	v_cndmask_b32_e64 v214, v95, v235, s[6:7]
	v_readlane_b32 s6, v253, 60
	v_readlane_b32 s7, v253, 61
	s_nop 1
	v_cndmask_b32_e64 v213, v96, v235, s[6:7]
	v_readlane_b32 s6, v253, 62
	v_readlane_b32 s7, v253, 63
	v_max3_f32 v4, v4, v214, v213
	s_nop 0
	v_cndmask_b32_e64 v212, v97, v235, s[6:7]
	v_readlane_b32 s6, v254, 0
	v_readlane_b32 s7, v254, 1
	s_nop 1
	v_cndmask_b32_e64 v211, v98, v235, s[6:7]
	v_readlane_b32 s6, v254, 2
	v_readlane_b32 s7, v254, 3
	v_max3_f32 v4, v4, v212, v211
	s_nop 0
	v_cndmask_b32_e64 v210, v99, v235, s[6:7]
	v_readlane_b32 s6, v254, 4
	v_readlane_b32 s7, v254, 5
	s_nop 1
	v_cndmask_b32_e64 v209, v100, v235, s[6:7]
	v_readlane_b32 s6, v254, 6
	v_readlane_b32 s7, v254, 7
	v_max3_f32 v4, v4, v210, v209
	s_nop 0
	v_cndmask_b32_e64 v208, v101, v235, s[6:7]
	v_readlane_b32 s6, v254, 8
	v_readlane_b32 s7, v254, 9
	s_nop 1
	v_cndmask_b32_e64 v207, v102, v235, s[6:7]
	v_readlane_b32 s6, v254, 10
	v_readlane_b32 s7, v254, 11
	v_max3_f32 v4, v4, v208, v207
	s_nop 0
	v_cndmask_b32_e64 v206, v103, v235, s[6:7]
	v_readlane_b32 s6, v254, 12
	v_readlane_b32 s7, v254, 13
	s_nop 1
	v_cndmask_b32_e64 v103, v104, v235, s[6:7]
	v_readlane_b32 s6, v254, 14
	v_readlane_b32 s7, v254, 15
	v_max3_f32 v4, v4, v206, v103
	s_nop 0
	v_cndmask_b32_e64 v102, v105, v235, s[6:7]
	v_readlane_b32 s6, v254, 16
	v_readlane_b32 s7, v254, 17
	s_nop 1
	v_cndmask_b32_e64 v101, v74, v235, s[6:7]
	v_readlane_b32 s6, v254, 18
	v_readlane_b32 s7, v254, 19
	v_max3_f32 v4, v4, v102, v101
	s_nop 0
	v_cndmask_b32_e64 v100, v75, v235, s[6:7]
	v_readlane_b32 s6, v254, 20
	v_readlane_b32 s7, v254, 21
	s_nop 1
	v_cndmask_b32_e64 v99, v76, v235, s[6:7]
	v_readlane_b32 s6, v254, 22
	v_readlane_b32 s7, v254, 23
	v_max3_f32 v4, v4, v100, v99
	s_nop 0
	v_cndmask_b32_e64 v98, v77, v235, s[6:7]
	v_readlane_b32 s6, v254, 24
	v_readlane_b32 s7, v254, 25
	s_nop 1
	v_cndmask_b32_e64 v97, v78, v235, s[6:7]
	v_readlane_b32 s6, v254, 26
	v_readlane_b32 s7, v254, 27
	v_max3_f32 v4, v4, v98, v97
	s_nop 0
	v_cndmask_b32_e64 v96, v79, v235, s[6:7]
	v_readlane_b32 s6, v254, 28
	v_readlane_b32 s7, v254, 29
	s_nop 1
	v_cndmask_b32_e64 v95, v80, v235, s[6:7]
	v_readlane_b32 s6, v254, 30
	v_readlane_b32 s7, v254, 31
	v_max3_f32 v4, v4, v96, v95
	s_nop 0
	v_cndmask_b32_e64 v94, v81, v235, s[6:7]
	v_readlane_b32 s6, v254, 32
	v_readlane_b32 s7, v254, 33
	s_nop 1
	v_cndmask_b32_e64 v93, v82, v235, s[6:7]
	v_readlane_b32 s6, v254, 34
	v_readlane_b32 s7, v254, 35
	v_max3_f32 v4, v4, v94, v93
	s_nop 0
	v_cndmask_b32_e64 v92, v83, v235, s[6:7]
	v_readlane_b32 s6, v254, 36
	v_readlane_b32 s7, v254, 37
	s_nop 1
	v_cndmask_b32_e64 v91, v84, v235, s[6:7]
	v_readlane_b32 s6, v254, 38
	v_readlane_b32 s7, v254, 39
	v_max3_f32 v4, v4, v92, v91
	s_nop 0
	v_cndmask_b32_e64 v90, v85, v235, s[6:7]
	v_readlane_b32 s6, v254, 40
	v_readlane_b32 s7, v254, 41
	s_nop 1
	v_cndmask_b32_e64 v85, v86, v235, s[6:7]
	v_readlane_b32 s6, v254, 42
	v_readlane_b32 s7, v254, 43
	v_max3_f32 v4, v4, v90, v85
	s_nop 0
	v_cndmask_b32_e64 v84, v87, v235, s[6:7]
	v_readlane_b32 s6, v254, 44
	v_readlane_b32 s7, v254, 45
	s_nop 1
	v_cndmask_b32_e64 v83, v88, v235, s[6:7]
	v_readlane_b32 s6, v254, 46
	v_readlane_b32 s7, v254, 47
	v_max3_f32 v4, v4, v84, v83
	s_nop 0
	v_cndmask_b32_e64 v82, v89, v235, s[6:7]
	v_readlane_b32 s6, v254, 48
	v_readlane_b32 s7, v254, 49
	s_nop 1
	v_cndmask_b32_e64 v81, v58, v235, s[6:7]
	v_readlane_b32 s6, v254, 50
	v_readlane_b32 s7, v254, 51
	v_max3_f32 v4, v4, v82, v81
	s_nop 0
	v_cndmask_b32_e64 v80, v59, v235, s[6:7]
	v_readlane_b32 s6, v254, 52
	v_readlane_b32 s7, v254, 53
	s_nop 1
	v_cndmask_b32_e64 v79, v60, v235, s[6:7]
	v_readlane_b32 s6, v254, 54
	v_readlane_b32 s7, v254, 55
	v_max3_f32 v4, v4, v80, v79
	s_nop 0
	v_cndmask_b32_e64 v78, v61, v235, s[6:7]
	v_readlane_b32 s6, v254, 56
	v_readlane_b32 s7, v254, 57
	s_nop 1
	v_cndmask_b32_e64 v77, v62, v235, s[6:7]
	v_readlane_b32 s6, v254, 58
	v_readlane_b32 s7, v254, 59
	v_max3_f32 v4, v4, v78, v77
	s_nop 0
	v_cndmask_b32_e64 v76, v63, v235, s[6:7]
	v_readlane_b32 s6, v254, 60
	v_readlane_b32 s7, v254, 61
	s_nop 1
	v_cndmask_b32_e64 v75, v64, v235, s[6:7]
	v_readlane_b32 s6, v254, 62
	v_readlane_b32 s7, v254, 63
	v_max3_f32 v4, v4, v76, v75
	s_nop 0
	v_cndmask_b32_e64 v74, v65, v235, s[6:7]
	v_readlane_b32 s6, v255, 0
	v_readlane_b32 s7, v255, 1
	s_nop 1
	v_cndmask_b32_e64 v66, v66, v235, s[6:7]
	v_readlane_b32 s6, v255, 2
	v_readlane_b32 s7, v255, 3
	v_max3_f32 v4, v4, v74, v66
	s_nop 0
	v_cndmask_b32_e64 v65, v67, v235, s[6:7]
	v_readlane_b32 s6, v255, 4
	v_readlane_b32 s7, v255, 5
	s_nop 1
	v_cndmask_b32_e64 v64, v68, v235, s[6:7]
	v_readlane_b32 s6, v255, 6
	v_readlane_b32 s7, v255, 7
	v_max3_f32 v4, v4, v65, v64
	s_nop 0
	v_cndmask_b32_e64 v63, v69, v235, s[6:7]
	v_readlane_b32 s6, v255, 8
	v_readlane_b32 s7, v255, 9
	s_nop 1
	v_cndmask_b32_e64 v62, v70, v235, s[6:7]
	v_readlane_b32 s6, v255, 10
	v_readlane_b32 s7, v255, 11
	v_max3_f32 v4, v4, v63, v62
	s_nop 0
	v_cndmask_b32_e64 v61, v71, v235, s[6:7]
	v_readlane_b32 s6, v255, 12
	v_readlane_b32 s7, v255, 13
	s_nop 1
	v_cndmask_b32_e64 v60, v72, v235, s[6:7]
	v_readlane_b32 s6, v255, 14
	v_readlane_b32 s7, v255, 15
	v_max3_f32 v4, v4, v61, v60
	s_nop 0
	v_cndmask_b32_e64 v59, v73, v235, s[6:7]
	v_readlane_b32 s6, v255, 16
	v_readlane_b32 s7, v255, 17
	s_nop 1
	v_cndmask_b32_e64 v58, v42, v235, s[6:7]
	v_readlane_b32 s6, v255, 18
	v_readlane_b32 s7, v255, 19
	v_max3_f32 v4, v4, v59, v58
	s_nop 0
	v_cndmask_b32_e64 v43, v43, v235, s[6:7]
	v_readlane_b32 s6, v255, 20
	v_readlane_b32 s7, v255, 21
	s_nop 1
	v_cndmask_b32_e64 v42, v44, v235, s[6:7]
	v_readlane_b32 s6, v255, 22
	v_readlane_b32 s7, v255, 23
	v_max3_f32 v4, v4, v43, v42
	s_nop 0
	v_cndmask_b32_e64 v17, v45, v235, s[6:7]
	v_readlane_b32 s6, v255, 24
	v_readlane_b32 s7, v255, 25
	v_xor_b32_e32 v45, 32, v221
	s_nop 0
	v_cndmask_b32_e64 v14, v46, v235, s[6:7]
	v_readlane_b32 s6, v255, 26
	v_readlane_b32 s7, v255, 27
	v_max3_f32 v6, v4, v17, v14
	v_and_b32_e32 v46, 64, v221
	v_cndmask_b32_e64 v4, v47, v235, s[6:7]
	v_readlane_b32 s6, v255, 28
	v_readlane_b32 s7, v255, 29
	v_add_u32_e32 v46, 64, v46
	v_cmp_lt_i32_e32 vcc, v45, v46
	v_cndmask_b32_e64 v5, v48, v235, s[6:7]
	v_readlane_b32 s6, v255, 30
	v_readlane_b32 s7, v255, 31
	v_max3_f32 v8, v6, v4, v5
	v_cndmask_b32_e32 v45, v221, v45, vcc
	v_cndmask_b32_e64 v6, v49, v235, s[6:7]
	v_readlane_b32 s6, v255, 32
	v_readlane_b32 s7, v255, 33
	v_lshlrev_b32_e32 v45, 2, v45
	s_nop 0
	v_cndmask_b32_e64 v7, v50, v235, s[6:7]
	v_readlane_b32 s6, v255, 34
	v_readlane_b32 s7, v255, 35
	v_max3_f32 v10, v8, v6, v7
	s_nop 0
	v_cndmask_b32_e64 v8, v51, v235, s[6:7]
	v_readlane_b32 s6, v255, 36
	v_readlane_b32 s7, v255, 37
	s_nop 1
	v_cndmask_b32_e64 v9, v52, v235, s[6:7]
	v_readlane_b32 s6, v255, 38
	v_readlane_b32 s7, v255, 39
	v_max3_f32 v12, v10, v8, v9
	s_nop 0
	v_cndmask_b32_e64 v10, v53, v235, s[6:7]
	v_readlane_b32 s6, v255, 40
	v_readlane_b32 s7, v255, 41
	s_nop 1
	v_cndmask_b32_e64 v11, v54, v235, s[6:7]
	v_readlane_b32 s6, v255, 42
	v_readlane_b32 s7, v255, 43
	v_max3_f32 v15, v12, v10, v11
	s_nop 0
	v_cndmask_b32_e64 v12, v55, v235, s[6:7]
	v_readlane_b32 s6, v255, 44
	v_readlane_b32 s7, v255, 45
	s_nop 1
	v_cndmask_b32_e64 v13, v56, v235, s[6:7]
	v_readlane_b32 s6, v255, 46
	v_readlane_b32 s7, v255, 47
	v_max3_f32 v44, v15, v12, v13
	s_nop 0
	v_cndmask_b32_e64 v15, v57, v235, s[6:7]
	v_readlane_b32 s6, v255, 48
	v_readlane_b32 s7, v255, 49
	s_nop 1
	v_cndmask_b32_e64 v0, v0, v235, s[6:7]
	v_readlane_b32 s6, v255, 50
	v_readlane_b32 s7, v255, 51
	v_max3_f32 v44, v44, v15, v0
	s_nop 0
	v_cndmask_b32_e64 v1, v1, v235, s[6:7]
	v_readlane_b32 s6, v255, 52
	v_readlane_b32 s7, v255, 53
	s_nop 1
	v_cndmask_b32_e64 v2, v2, v235, s[6:7]
	v_readlane_b32 s6, v255, 54
	v_readlane_b32 s7, v255, 55
	v_max3_f32 v44, v44, v1, v2
	s_nop 0
	v_cndmask_b32_e64 v3, v3, v235, s[6:7]
	s_mov_b32 s6, 0xff800000
	v_max3_f32 v44, v44, v3, s6
	s_lshl_b32 s7, s54, 2
	s_load_dword s7, s[62:63], s7
	ds_bpermute_b32 v46, v45, v44
	s_mov_b32 s6, 0x3fb8aa3b
	s_waitcnt lgkmcnt(0)
	v_mov_b32_e32 v47, s7
	v_mul_f32_e32 v48, 0x3fb8aa3b, v47
	v_max3_f32 v54, v44, v46, v48
	v_sub_f32_e32 v44, v222, v54
	v_exp_f32_e32 v44, v44
	v_sub_f32_e32 v46, v236, v54
	v_exp_f32_e32 v46, v46
	v_sub_f32_e32 v56, v211, v54
	v_add_f32_e32 v48, 0, v44
	v_exp_f32_e32 v67, v56
	v_add_f32_e32 v49, v46, v48
	v_sub_f32_e32 v48, v217, v54
	v_exp_f32_e32 v48, v48
	v_sub_f32_e32 v56, v210, v54
	v_exp_f32_e32 v69, v56
	v_sub_f32_e32 v56, v209, v54
	v_add_f32_e32 v50, v48, v49
	v_sub_f32_e32 v49, v216, v54
	v_exp_f32_e32 v49, v49
	v_exp_f32_e32 v71, v56
	v_sub_f32_e32 v56, v208, v54
	v_exp_f32_e32 v73, v56
	v_add_f32_e32 v51, v49, v50
	v_sub_f32_e32 v50, v215, v54
	v_exp_f32_e32 v50, v50
	v_sub_f32_e32 v56, v207, v54
	v_exp_f32_e32 v88, v56
	v_sub_f32_e32 v56, v206, v54
	v_add_f32_e32 v52, v50, v51
	v_sub_f32_e32 v51, v214, v54
	v_exp_f32_e32 v51, v51
	v_exp_f32_e32 v104, v56
	v_sub_f32_e32 v56, v103, v54
	v_exp_f32_e32 v103, v56
	v_add_f32_e32 v53, v51, v52
	v_sub_f32_e32 v52, v213, v54
	v_exp_f32_e32 v52, v52
	v_sub_f32_e32 v56, v102, v54
	v_exp_f32_e32 v102, v56
	v_sub_f32_e32 v56, v101, v54
	v_add_f32_e32 v55, v52, v53
	v_sub_f32_e32 v53, v212, v54
	v_exp_f32_e32 v53, v53
	v_exp_f32_e32 v68, v56
	v_sub_f32_e32 v56, v100, v54
	v_exp_f32_e32 v72, v56
	v_add_f32_e32 v55, v53, v55
	v_add_f32_e32 v55, v67, v55
	v_add_f32_e32 v55, v69, v55
	v_add_f32_e32 v55, v71, v55
	v_add_f32_e32 v55, v73, v55
	v_add_f32_e32 v55, v88, v55
	v_add_f32_e32 v55, v104, v55
	v_sub_f32_e32 v56, v99, v54
	v_add_f32_e32 v55, v103, v55
	v_exp_f32_e32 v86, v56
	v_sub_f32_e32 v56, v98, v54
	v_add_f32_e32 v55, v102, v55
	v_exp_f32_e32 v89, v56
	v_sub_f32_e32 v56, v97, v54
	v_add_f32_e32 v55, v68, v55
	v_exp_f32_e32 v97, v56
	v_sub_f32_e32 v56, v96, v54
	v_add_f32_e32 v55, v72, v55
	v_exp_f32_e32 v96, v56
	v_sub_f32_e32 v56, v95, v54
	v_add_f32_e32 v55, v86, v55
	v_exp_f32_e32 v95, v56
	v_sub_f32_e32 v56, v94, v54
	v_add_f32_e32 v55, v89, v55
	v_exp_f32_e32 v101, v56
	v_sub_f32_e32 v56, v93, v54
	v_add_f32_e32 v55, v97, v55
	v_exp_f32_e32 v70, v56
	v_sub_f32_e32 v56, v92, v54
	v_add_f32_e32 v55, v96, v55
	v_exp_f32_e32 v87, v56
	v_sub_f32_e32 v56, v91, v54
	v_add_f32_e32 v55, v95, v55
	v_exp_f32_e32 v91, v56
	v_sub_f32_e32 v56, v90, v54
	v_add_f32_e32 v55, v101, v55
	v_exp_f32_e32 v90, v56
	v_sub_f32_e32 v56, v85, v54
	v_add_f32_e32 v55, v70, v55
	v_exp_f32_e32 v85, v56
	v_sub_f32_e32 v56, v84, v54
	v_add_f32_e32 v55, v87, v55
	v_exp_f32_e32 v100, v56
	v_sub_f32_e32 v56, v83, v54
	v_add_f32_e32 v55, v91, v55
	v_exp_f32_e32 v206, v56
	v_sub_f32_e32 v56, v82, v54
	v_add_f32_e32 v55, v90, v55
	v_exp_f32_e32 v209, v56
	v_sub_f32_e32 v56, v81, v54
	v_add_f32_e32 v55, v85, v55
	v_exp_f32_e32 v81, v56
	v_sub_f32_e32 v56, v80, v54
	v_add_f32_e32 v55, v100, v55
	v_exp_f32_e32 v80, v56
	v_sub_f32_e32 v56, v79, v54
	v_add_f32_e32 v55, v206, v55
	v_exp_f32_e32 v79, v56
	v_sub_f32_e32 v56, v78, v54
	v_add_f32_e32 v55, v209, v55
	v_exp_f32_e32 v84, v56
	v_sub_f32_e32 v56, v77, v54
	v_add_f32_e32 v55, v81, v55
	v_exp_f32_e32 v94, v56
	v_sub_f32_e32 v56, v76, v54
	v_add_f32_e32 v55, v80, v55
	v_exp_f32_e32 v208, v56
	v_sub_f32_e32 v56, v75, v54
	v_add_f32_e32 v55, v79, v55
	v_exp_f32_e32 v211, v56
	v_sub_f32_e32 v56, v74, v54
	v_add_f32_e32 v55, v84, v55
	v_exp_f32_e32 v213, v56
	v_sub_f32_e32 v56, v66, v54
	v_add_f32_e32 v55, v94, v55
	v_exp_f32_e32 v66, v56
	v_sub_f32_e32 v56, v65, v54
	v_add_f32_e32 v55, v208, v55
	v_exp_f32_e32 v82, v56
	v_sub_f32_e32 v56, v64, v54
	v_add_f32_e32 v55, v211, v55
	v_exp_f32_e32 v92, v56
	v_sub_f32_e32 v56, v63, v54
	v_add_f32_e32 v55, v213, v55
	v_exp_f32_e32 v98, v56
	v_sub_f32_e32 v56, v62, v54
	v_add_f32_e32 v55, v66, v55
	v_exp_f32_e32 v105, v56
	v_sub_f32_e32 v56, v61, v54
	v_add_f32_e32 v55, v82, v55
	v_exp_f32_e32 v212, v56
	v_sub_f32_e32 v56, v60, v54
	v_add_f32_e32 v55, v92, v55
	v_exp_f32_e32 v215, v56
	v_sub_f32_e32 v56, v59, v54
	v_add_f32_e32 v55, v98, v55
	v_exp_f32_e32 v222, v56
	v_sub_f32_e32 v56, v58, v54
	v_add_f32_e32 v55, v105, v55
	v_exp_f32_e32 v76, v56
	v_sub_f32_e32 v43, v43, v54
	v_add_f32_e32 v55, v212, v55
	v_exp_f32_e32 v93, v43
	v_sub_f32_e32 v42, v42, v54
	v_add_f32_e32 v55, v215, v55
	v_exp_f32_e32 v99, v42
	v_sub_f32_e32 v17, v17, v54
	v_add_f32_e32 v55, v222, v55
	v_exp_f32_e32 v207, v17
	v_sub_f32_e32 v14, v14, v54
	v_add_f32_e32 v55, v76, v55
	v_exp_f32_e32 v210, v14
	v_sub_f32_e32 v4, v4, v54
	v_add_f32_e32 v43, v93, v55
	v_exp_f32_e32 v214, v4
	v_sub_f32_e32 v5, v5, v54
	v_add_f32_e32 v42, v99, v43
	v_exp_f32_e32 v216, v5
	v_sub_f32_e32 v5, v6, v54
	v_add_f32_e32 v17, v207, v42
	v_exp_f32_e32 v217, v5
	v_sub_f32_e32 v5, v7, v54
	v_add_f32_e32 v14, v210, v17
	v_exp_f32_e32 v63, v5
	v_sub_f32_e32 v5, v8, v54
	v_add_f32_e32 v4, v214, v14
	v_exp_f32_e32 v64, v5
	v_sub_f32_e32 v5, v9, v54
	v_add_f32_e32 v4, v216, v4
	v_exp_f32_e32 v65, v5
	v_sub_f32_e32 v5, v10, v54
	v_add_f32_e32 v4, v217, v4
	v_exp_f32_e32 v74, v5
	v_sub_f32_e32 v5, v11, v54
	v_add_f32_e32 v4, v63, v4
	v_exp_f32_e32 v75, v5
	v_sub_f32_e32 v5, v12, v54
	v_add_f32_e32 v4, v64, v4
	v_exp_f32_e32 v77, v5
	v_sub_f32_e32 v5, v13, v54
	v_add_f32_e32 v4, v65, v4
	v_exp_f32_e32 v78, v5
	v_sub_f32_e32 v5, v15, v54
	v_add_f32_e32 v4, v74, v4
	v_exp_f32_e32 v83, v5
	v_sub_f32_e32 v0, v0, v54
	v_add_f32_e32 v4, v75, v4
	v_exp_f32_e32 v59, v0
	v_sub_f32_e32 v1, v1, v54
	v_add_f32_e32 v4, v77, v4
	v_exp_f32_e32 v60, v1
	v_sub_f32_e32 v1, v2, v54
	v_add_f32_e32 v4, v78, v4
	v_exp_f32_e32 v61, v1
	v_sub_f32_e32 v1, v3, v54
	v_add_f32_e32 v4, v83, v4
	v_exp_f32_e32 v62, v1
	v_sub_f32_e32 v1, 0xff800000, v54
	v_add_f32_e32 v0, v59, v4
	v_exp_f32_e32 v58, v1
	v_add_f32_e32 v0, v60, v0
	v_add_f32_e32 v0, v61, v0
	v_add_f32_e32 v0, v62, v0
	v_add_f32_e32 v0, v58, v0
	v_add_f32_e32 v0, v58, v0
	v_add_f32_e32 v0, v58, v0
	v_add_f32_e32 v0, v58, v0
	v_add_f32_e32 v0, v58, v0
	v_add_f32_e32 v0, v58, v0
	v_add_f32_e32 v0, v58, v0
	v_add_f32_e32 v0, v58, v0
	v_add_f32_e32 v0, v58, v0
	v_add_f32_e32 v0, v58, v0
	v_add_f32_e32 v0, v58, v0
	v_add_f32_e32 v0, v58, v0
	ds_bpermute_b32 v1, v45, v0
	s_waitcnt lgkmcnt(0)
	v_add_f32_e32 v0, v0, v1
	v_fma_f32 v1, v47, s6, -v54
	v_exp_f32_e32 v1, v1
	s_nop 0
	v_add_f32_e32 v17, v1, v0
	v_cvt_pk_bf16_f32 v0, v44, v46
	v_cvt_pk_bf16_f32 v1, v48, v49
	v_cvt_pk_bf16_f32 v2, v50, v51
	v_cvt_pk_bf16_f32 v3, v52, v53
	ds_read_b64_tr_b16 v[4:5], v155 offset:61440
	ds_read_b64_tr_b16 v[6:7], v155 offset:62976
	s_waitcnt lgkmcnt(0)
	v_mfma_f32_32x32x16_bf16 v[42:57], v[4:7], v[0:3], 0
	ds_read_b64_tr_b16 v[4:5], v155 offset:61504
	ds_read_b64_tr_b16 v[6:7], v155 offset:63040
	v_cvt_pk_bf16_f32 v224, v67, v69
	v_cvt_pk_bf16_f32 v225, v71, v73
	v_cvt_pk_bf16_f32 v226, v88, v104
	v_cvt_pk_bf16_f32 v227, v103, v102
	ds_read_b64_tr_b16 v[236:237], v155 offset:64512
	ds_read_b64_tr_b16 v[238:239], v156 offset:4608
	v_rcp_f32_e32 v17, v17
	s_waitcnt lgkmcnt(2)
	v_mfma_f32_32x32x16_bf16 v[0:15], v[4:7], v[0:3], 0
	s_waitcnt lgkmcnt(0)
	v_mfma_f32_32x32x16_bf16 v[42:57], v[236:239], v[224:227], v[42:57]
	ds_read_b64_tr_b16 v[236:237], v155 offset:64576
	ds_read_b64_tr_b16 v[238:239], v156 offset:4672
	s_waitcnt lgkmcnt(0)
	v_mfma_f32_32x32x16_bf16 v[0:15], v[236:239], v[224:227], v[0:15]
	v_cvt_pk_bf16_f32 v224, v68, v72
	v_cvt_pk_bf16_f32 v225, v86, v89
	v_cvt_pk_bf16_f32 v226, v97, v96
	v_cvt_pk_bf16_f32 v227, v95, v101
	ds_read_b64_tr_b16 v[236:237], v156 offset:6144
	ds_read_b64_tr_b16 v[238:239], v156 offset:7680
	s_waitcnt lgkmcnt(0)
	v_mfma_f32_32x32x16_bf16 v[42:57], v[236:239], v[224:227], v[42:57]
	ds_read_b64_tr_b16 v[236:237], v156 offset:6208
	ds_read_b64_tr_b16 v[238:239], v156 offset:7744
	v_cvt_pk_bf16_f32 v68, v70, v87
	v_cvt_pk_bf16_f32 v69, v91, v90
	v_cvt_pk_bf16_f32 v70, v85, v100
	v_cvt_pk_bf16_f32 v71, v206, v209
	ds_read_b64_tr_b16 v[86:87], v156 offset:9216
	ds_read_b64_tr_b16 v[88:89], v156 offset:10752
	s_waitcnt lgkmcnt(2)
	v_mfma_f32_32x32x16_bf16 v[0:15], v[236:239], v[224:227], v[0:15]
	s_waitcnt lgkmcnt(0)
	v_mfma_f32_32x32x16_bf16 v[42:57], v[86:89], v[68:71], v[42:57]
	ds_read_b64_tr_b16 v[86:87], v156 offset:9280
	ds_read_b64_tr_b16 v[88:89], v156 offset:10816
	s_waitcnt lgkmcnt(0)
	v_mfma_f32_32x32x16_bf16 v[0:15], v[86:89], v[68:71], v[0:15]
	v_cvt_pk_bf16_f32 v68, v81, v80
	v_cvt_pk_bf16_f32 v69, v79, v84
	v_cvt_pk_bf16_f32 v70, v94, v208
	v_cvt_pk_bf16_f32 v71, v211, v213
	ds_read_b64_tr_b16 v[84:85], v156 offset:12288
	ds_read_b64_tr_b16 v[86:87], v156 offset:13824
	s_waitcnt lgkmcnt(0)
	v_mfma_f32_32x32x16_bf16 v[42:57], v[84:87], v[68:71], v[42:57]
	ds_read_b64_tr_b16 v[84:85], v156 offset:12352
	ds_read_b64_tr_b16 v[86:87], v156 offset:13888
	v_cvt_pk_bf16_f32 v66, v66, v82
	v_cvt_pk_bf16_f32 v67, v92, v98
	s_waitcnt lgkmcnt(0)
	v_mfma_f32_32x32x16_bf16 v[0:15], v[84:87], v[68:71], v[0:15]
	v_cvt_pk_bf16_f32 v68, v105, v212
	v_cvt_pk_bf16_f32 v69, v215, v222
	ds_read_b64_tr_b16 v[70:71], v156 offset:15360
	ds_read_b64_tr_b16 v[72:73], v156 offset:16896
	s_waitcnt lgkmcnt(0)
	v_mfma_f32_32x32x16_bf16 v[42:57], v[70:73], v[66:69], v[42:57]
	ds_read_b64_tr_b16 v[70:71], v156 offset:15424
	ds_read_b64_tr_b16 v[72:73], v156 offset:16960
	s_waitcnt lgkmcnt(0)
	v_mfma_f32_32x32x16_bf16 v[0:15], v[70:73], v[66:69], v[0:15]
	v_cvt_pk_bf16_f32 v66, v76, v93
	v_cvt_pk_bf16_f32 v67, v99, v207
	v_cvt_pk_bf16_f32 v68, v210, v214
	v_cvt_pk_bf16_f32 v69, v216, v217
	ds_read_b64_tr_b16 v[70:71], v156 offset:18432
	ds_read_b64_tr_b16 v[72:73], v156 offset:19968
	s_waitcnt lgkmcnt(0)
	v_mfma_f32_32x32x16_bf16 v[42:57], v[70:73], v[66:69], v[42:57]
	ds_read_b64_tr_b16 v[70:71], v156 offset:18496
	ds_read_b64_tr_b16 v[72:73], v156 offset:20032
	v_cvt_pk_bf16_f32 v64, v63, v64
	v_cvt_pk_bf16_f32 v65, v65, v74
	s_waitcnt lgkmcnt(0)
	v_mfma_f32_32x32x16_bf16 v[0:15], v[70:73], v[66:69], v[0:15]
	v_cvt_pk_bf16_f32 v66, v75, v77
	v_cvt_pk_bf16_f32 v67, v78, v83
	ds_read_b64_tr_b16 v[68:69], v156 offset:21504
	ds_read_b64_tr_b16 v[70:71], v156 offset:23040
	s_waitcnt lgkmcnt(0)
	v_mfma_f32_32x32x16_bf16 v[42:57], v[68:71], v[64:67], v[42:57]
	ds_read_b64_tr_b16 v[68:69], v156 offset:21568
	ds_read_b64_tr_b16 v[70:71], v156 offset:23104
	v_cvt_pk_bf16_f32 v60, v59, v60
	v_cvt_pk_bf16_f32 v61, v61, v62
	v_cvt_pk_bf16_f32 v62, v58, v58
	v_cvt_pk_bf16_f32 v63, v58, v58
	s_waitcnt lgkmcnt(0)
	v_mfma_f32_32x32x16_bf16 v[0:15], v[68:71], v[64:67], v[0:15]
	ds_read_b64_tr_b16 v[64:65], v156 offset:24576
	ds_read_b64_tr_b16 v[66:67], v156 offset:26112
	s_waitcnt lgkmcnt(0)
	v_mfma_f32_32x32x16_bf16 v[42:57], v[64:67], v[60:63], v[42:57]
	ds_read_b64_tr_b16 v[64:65], v156 offset:24640
	ds_read_b64_tr_b16 v[66:67], v156 offset:26176
	s_waitcnt lgkmcnt(0)
	v_mfma_f32_32x32x16_bf16 v[0:15], v[64:67], v[60:63], v[0:15]
	v_cvt_pk_bf16_f32 v60, v58, v58
	v_cvt_pk_bf16_f32 v61, v58, v58
	v_cvt_pk_bf16_f32 v62, v58, v58
	v_cvt_pk_bf16_f32 v63, v58, v58
	ds_read_b64_tr_b16 v[64:65], v156 offset:27648
	ds_read_b64_tr_b16 v[66:67], v156 offset:29184
	s_waitcnt lgkmcnt(0)
	v_mfma_f32_32x32x16_bf16 v[42:57], v[64:67], v[60:63], v[42:57]
	ds_read_b64_tr_b16 v[64:65], v156 offset:27712
	ds_read_b64_tr_b16 v[66:67], v156 offset:29248
	s_waitcnt lgkmcnt(0)
	v_mfma_f32_32x32x16_bf16 v[0:15], v[64:67], v[60:63], v[0:15]
	s_nop 7
	v_mul_f32_e32 v42, v42, v17
	v_mul_f32_e32 v43, v43, v17
	v_cvt_pk_bf16_f32 v42, v42, v43
	v_mul_f32_e32 v43, v44, v17
	v_mul_f32_e32 v44, v45, v17
	v_cvt_pk_bf16_f32 v43, v43, v44
	v_add_u32_e32 v44, v157, v126
	ds_write_b64 v44, v[42:43]
	v_mul_f32_e32 v42, v46, v17
	v_mul_f32_e32 v43, v47, v17
	v_cvt_pk_bf16_f32 v42, v42, v43
	v_mul_f32_e32 v43, v48, v17
	v_mul_f32_e32 v44, v49, v17
	v_cvt_pk_bf16_f32 v43, v43, v44
	v_add_u32_e32 v44, v157, v158
	ds_write_b64 v44, v[42:43]
	v_mul_f32_e32 v42, v50, v17
	v_mul_f32_e32 v43, v51, v17
	v_cvt_pk_bf16_f32 v42, v42, v43
	v_mul_f32_e32 v43, v52, v17
	v_mul_f32_e32 v44, v53, v17
	v_cvt_pk_bf16_f32 v43, v43, v44
	v_add_u32_e32 v44, v157, v159
	ds_write_b64 v44, v[42:43]
	v_mul_f32_e32 v42, v54, v17
	v_mul_f32_e32 v43, v55, v17
	v_cvt_pk_bf16_f32 v42, v42, v43
	v_mul_f32_e32 v43, v56, v17
	v_mul_f32_e32 v44, v57, v17
	v_cvt_pk_bf16_f32 v43, v43, v44
	v_add_u32_e32 v44, v157, v160
	v_mul_f32_e32 v0, v0, v17
	v_mul_f32_e32 v1, v1, v17
	ds_write_b64 v44, v[42:43]
	v_cvt_pk_bf16_f32 v0, v0, v1
	v_mul_f32_e32 v1, v2, v17
	v_mul_f32_e32 v2, v3, v17
	v_cvt_pk_bf16_f32 v1, v1, v2
	v_add_u32_e32 v2, v157, v161
	ds_write_b64 v2, v[0:1]
	v_mul_f32_e32 v0, v4, v17
	v_mul_f32_e32 v1, v5, v17
	v_cvt_pk_bf16_f32 v0, v0, v1
	v_mul_f32_e32 v1, v6, v17
	v_mul_f32_e32 v2, v7, v17
	v_cvt_pk_bf16_f32 v1, v1, v2
	v_add_u32_e32 v2, v157, v162
	ds_write_b64 v2, v[0:1]
	v_mul_f32_e32 v0, v8, v17
	v_mul_f32_e32 v1, v9, v17
	v_cvt_pk_bf16_f32 v0, v0, v1
	v_mul_f32_e32 v1, v10, v17
	v_mul_f32_e32 v2, v11, v17
	v_cvt_pk_bf16_f32 v1, v1, v2
	v_add_u32_e32 v2, v157, v163
	ds_write_b64 v2, v[0:1]
	v_mul_f32_e32 v0, v12, v17
	v_mul_f32_e32 v1, v13, v17
	v_cvt_pk_bf16_f32 v0, v0, v1
	v_mul_f32_e32 v1, v14, v17
	v_mul_f32_e32 v2, v15, v17
	v_cvt_pk_bf16_f32 v1, v1, v2
	v_add_u32_e32 v2, v157, v164
	ds_write_b64 v2, v[0:1]
	s_waitcnt lgkmcnt(0)
	s_mov_b64 s[6:7], exec
	v_readlane_b32 s56, v255, 56
	v_readlane_b32 s57, v255, 57
	s_and_b64 s[56:57], s[6:7], s[56:57]
	s_mov_b64 exec, s[56:57]
	s_cbranch_execz .LBB0_1260
	s_lshl_b32 s54, s54, 7
	v_lshl_add_u64 v[0:1], v[132:133], 0, s[54:55]
	s_and_b32 s54, s58, 0x7ffffffc
	s_addk_i32 s54, 0xfc00
	v_or_b32_e32 v2, 0x4000, v134
	v_add_u32_e32 v2, s54, v2
	v_mov_b32_e32 v3, v16
	v_lshlrev_b64 v[2:3], 11, v[2:3]
	v_lshl_add_u64 v[4:5], v[0:1], 0, v[2:3]
	v_add_u32_e32 v0, v165, v166
	ds_read_b128 v[0:3], v0
	s_waitcnt lgkmcnt(0)
	global_store_dwordx4 v[4:5], v[0:3], off

.LBB0_1262:
	s_andn2_b64 vcc, exec, s[56:57]
	s_cbranch_vccnz .LBB0_1216
	ds_read_b128 v[42:45], v201
	ds_read_b128 v[206:209], v201 offset:32
	ds_read_b128 v[210:213], v201 offset:64
	ds_read_b128 v[214:217], v201 offset:96
	ds_read_b128 v[0:3], v202 offset:33792
	ds_read_b128 v[4:7], v202 offset:33824
	s_and_b32 s54, s67, 0xfc0
	s_sub_i32 s6, 0x80, s54
	v_max_i32_e32 v238, s6, v167
	s_waitcnt lgkmcnt(1)
	v_mfma_f32_32x32x16_bf16 v[90:105], v[0:3], v[42:45], 0
	ds_read_b128 v[0:3], v202 offset:33856
	ds_read_b128 v[46:49], v202 offset:47648
	v_cmp_ge_u32_e32 vcc, v168, v238
	v_or_b32_e32 v17, 1, v168
	s_lshl_b32 s6, s61, 2
	s_add_i32 s56, s6, s33
	s_ashr_i32 s6, s59, 7
	s_waitcnt lgkmcnt(2)
	v_mfma_f32_32x32x16_bf16 v[90:105], v[4:7], v[206:209], v[90:105]
	s_ashr_i32 s7, s6, 31
	s_lshl_b64 s[6:7], s[6:7], 12
	s_or_b32 s6, s6, s54
	s_mov_b32 s54, 0xff800000
	s_ashr_i32 s57, s56, 31
	s_or_b64 s[6:7], s[6:7], s[4:5]
	s_lshl_b64 s[74:75], s[56:57], 2
	s_add_u32 s74, s62, s74
	s_addc_u32 s75, s63, s75
	s_load_dword s74, s[74:75], 0x0
	s_waitcnt lgkmcnt(1)
	v_mfma_f32_32x32x16_bf16 v[90:105], v[0:3], v[210:213], v[90:105]
	ds_read_b128 v[0:3], v202 offset:33888
	ds_read_b128 v[240:243], v202 offset:52256
	s_waitcnt lgkmcnt(1)
	v_mfma_f32_32x32x16_bf16 v[90:105], v[0:3], v[214:217], v[90:105]
	ds_read_b128 v[0:3], v202 offset:38400
	s_waitcnt lgkmcnt(0)
	v_mfma_f32_32x32x16_bf16 v[74:89], v[0:3], v[42:45], 0
	ds_read_b128 v[0:3], v202 offset:38432
	s_nop 7
	v_cndmask_b32_e32 v222, v235, v90, vcc
	v_cmp_ge_u32_e32 vcc, v17, v238
	v_or_b32_e32 v90, 2, v168
	s_waitcnt lgkmcnt(0)
	v_mfma_f32_32x32x16_bf16 v[74:89], v[0:3], v[206:209], v[74:89]
	ds_read_b128 v[0:3], v202 offset:38464
	s_waitcnt lgkmcnt(0)
	v_mfma_f32_32x32x16_bf16 v[74:89], v[0:3], v[210:213], v[74:89]
	ds_read_b128 v[0:3], v202 offset:38496
	s_waitcnt lgkmcnt(0)
	v_mfma_f32_32x32x16_bf16 v[74:89], v[0:3], v[214:217], v[74:89]
	ds_read_b128 v[0:3], v202 offset:43008
	s_waitcnt lgkmcnt(0)
	v_mfma_f32_32x32x16_bf16 v[58:73], v[0:3], v[42:45], 0
	ds_read_b128 v[0:3], v202 offset:43040
	s_waitcnt lgkmcnt(0)
	v_mfma_f32_32x32x16_bf16 v[58:73], v[0:3], v[206:209], v[58:73]
	ds_read_b128 v[0:3], v202 offset:43072
	s_waitcnt lgkmcnt(0)
	v_mfma_f32_32x32x16_bf16 v[58:73], v[0:3], v[210:213], v[58:73]
	ds_read_b128 v[0:3], v202 offset:43104
	s_waitcnt lgkmcnt(0)
	v_mfma_f32_32x32x16_bf16 v[58:73], v[0:3], v[214:217], v[58:73]
	ds_read_b128 v[0:3], v202 offset:47616
	s_waitcnt lgkmcnt(0)
	v_mfma_f32_32x32x16_bf16 v[0:15], v[0:3], v[42:45], 0
	v_mfma_f32_32x32x16_bf16 v[0:15], v[46:49], v[206:209], v[0:15]
	ds_read_b128 v[46:49], v202 offset:47680
	s_waitcnt lgkmcnt(0)
	v_mfma_f32_32x32x16_bf16 v[0:15], v[46:49], v[210:213], v[0:15]
	ds_read_b128 v[46:49], v202 offset:47712
	s_waitcnt lgkmcnt(0)
	v_mfma_f32_32x32x16_bf16 v[0:15], v[46:49], v[214:217], v[0:15]
	ds_read_b128 v[46:49], v202 offset:52224
	s_waitcnt lgkmcnt(0)
	v_mfma_f32_32x32x16_bf16 v[42:57], v[46:49], v[42:45], 0
	v_mfma_f32_32x32x16_bf16 v[42:57], v[240:243], v[206:209], v[42:57]
	ds_read_b128 v[206:209], v202 offset:52288
	s_waitcnt lgkmcnt(0)
	v_mfma_f32_32x32x16_bf16 v[42:57], v[206:209], v[210:213], v[42:57]
	ds_read_b128 v[206:209], v202 offset:52320
	s_waitcnt lgkmcnt(0)
	v_mfma_f32_32x32x16_bf16 v[42:57], v[206:209], v[214:217], v[42:57]
	v_cndmask_b32_e32 v217, v235, v91, vcc
	v_cmp_ge_u32_e32 vcc, v90, v238
	v_or_b32_e32 v90, 3, v168
	v_max3_f32 v17, v222, s54, v217
	v_cndmask_b32_e32 v236, v235, v92, vcc
	v_cmp_ge_u32_e32 vcc, v90, v238
	v_or_b32_e32 v90, 8, v168
	s_nop 4
	v_cndmask_b32_e64 v44, v44, v235, s[84:85]
	v_cndmask_b32_e32 v237, v235, v93, vcc
	v_cmp_ge_u32_e32 vcc, v90, v238
	v_or_b32_e32 v90, 9, v168
	v_max3_f32 v17, v17, v236, v237
	v_cndmask_b32_e32 v216, v235, v94, vcc
	v_cmp_ge_u32_e32 vcc, v90, v238
	v_or_b32_e32 v90, 10, v168
	s_mov_b32 s54, 0x3fb8aa3b
	v_cndmask_b32_e32 v214, v235, v95, vcc
	v_cmp_ge_u32_e32 vcc, v90, v238
	v_or_b32_e32 v90, 11, v168
	v_max3_f32 v17, v17, v216, v214
	v_cndmask_b32_e32 v215, v235, v96, vcc
	v_cmp_ge_u32_e32 vcc, v90, v238
	v_or_b32_e32 v90, 16, v168
	s_nop 0
	v_cndmask_b32_e32 v213, v235, v97, vcc
	v_cmp_ge_u32_e32 vcc, v90, v238
	v_or_b32_e32 v90, 17, v168
	v_max3_f32 v17, v17, v215, v213
	v_cndmask_b32_e32 v212, v235, v98, vcc
	v_cmp_ge_u32_e32 vcc, v90, v238
	v_or_b32_e32 v90, 18, v168
	s_nop 0
	v_cndmask_b32_e32 v210, v235, v99, vcc
	v_cmp_ge_u32_e32 vcc, v90, v238
	v_or_b32_e32 v90, 19, v168
	v_max3_f32 v17, v17, v212, v210
	v_cndmask_b32_e32 v211, v235, v100, vcc
	v_cmp_ge_u32_e32 vcc, v90, v238
	v_or_b32_e32 v90, 24, v168
	s_nop 0
	v_cndmask_b32_e32 v209, v235, v101, vcc
	v_cmp_ge_u32_e32 vcc, v90, v238
	v_or_b32_e32 v90, 25, v168
	v_max3_f32 v17, v17, v211, v209
	v_cndmask_b32_e32 v208, v235, v102, vcc
	v_cmp_ge_u32_e32 vcc, v90, v238
	v_or_b32_e32 v90, 26, v168
	s_nop 0
	v_cndmask_b32_e32 v206, v235, v103, vcc
	v_cmp_ge_u32_e32 vcc, v90, v238
	v_or_b32_e32 v90, 27, v168
	v_max3_f32 v17, v17, v208, v206
	v_cndmask_b32_e32 v207, v235, v104, vcc
	v_cmp_ge_u32_e32 vcc, v90, v238
	v_add_u32_e32 v90, 32, v168
	s_nop 0
	v_cndmask_b32_e32 v105, v235, v105, vcc
	v_cmp_ge_u32_e32 vcc, v90, v238
	v_max3_f32 v17, v17, v207, v105
	s_nop 0
	v_cndmask_b32_e32 v104, v235, v74, vcc
	v_add_u32_e32 v74, 33, v168
	v_cmp_ge_u32_e32 vcc, v74, v238
	v_add_u32_e32 v74, 34, v168
	s_nop 0
	v_cndmask_b32_e32 v102, v235, v75, vcc
	v_cmp_ge_u32_e32 vcc, v74, v238
	v_add_u32_e32 v74, 35, v168
	v_max3_f32 v17, v17, v104, v102
	v_cndmask_b32_e32 v103, v235, v76, vcc
	v_cmp_ge_u32_e32 vcc, v74, v238
	v_add_u32_e32 v74, 40, v168
	s_nop 0
	v_cndmask_b32_e32 v101, v235, v77, vcc
	v_cmp_ge_u32_e32 vcc, v74, v238
	v_add_u32_e32 v74, 41, v168
	v_max3_f32 v17, v17, v103, v101
	v_cndmask_b32_e32 v100, v235, v78, vcc
	v_cmp_ge_u32_e32 vcc, v74, v238
	v_add_u32_e32 v74, 42, v168
	s_nop 0
	v_cndmask_b32_e32 v98, v235, v79, vcc
	v_cmp_ge_u32_e32 vcc, v74, v238
	v_add_u32_e32 v74, 43, v168
	v_max3_f32 v17, v17, v100, v98
	v_cndmask_b32_e32 v99, v235, v80, vcc
	v_cmp_ge_u32_e32 vcc, v74, v238
	v_add_u32_e32 v74, 48, v168
	s_nop 0
	v_cndmask_b32_e32 v97, v235, v81, vcc
	v_cmp_ge_u32_e32 vcc, v74, v238
	v_add_u32_e32 v74, 49, v168
	v_max3_f32 v17, v17, v99, v97
	v_cndmask_b32_e32 v96, v235, v82, vcc
	v_cmp_ge_u32_e32 vcc, v74, v238
	v_add_u32_e32 v74, 50, v168
	s_nop 0
	v_cndmask_b32_e32 v94, v235, v83, vcc
	v_cmp_ge_u32_e32 vcc, v74, v238
	v_add_u32_e32 v74, 51, v168
	v_max3_f32 v17, v17, v96, v94
	v_cndmask_b32_e32 v95, v235, v84, vcc
	v_cmp_ge_u32_e32 vcc, v74, v238
	v_add_u32_e32 v74, 56, v168
	s_nop 0
	v_cndmask_b32_e32 v93, v235, v85, vcc
	v_cmp_ge_u32_e32 vcc, v74, v238
	v_add_u32_e32 v74, 57, v168
	v_max3_f32 v17, v17, v95, v93
	v_cndmask_b32_e32 v92, v235, v86, vcc
	v_cmp_ge_u32_e32 vcc, v74, v238
	v_add_u32_e32 v74, 58, v168
	s_nop 0
	v_cndmask_b32_e32 v90, v235, v87, vcc
	v_cmp_ge_u32_e32 vcc, v74, v238
	v_add_u32_e32 v74, 59, v168
	v_max3_f32 v17, v17, v92, v90
	v_cndmask_b32_e32 v91, v235, v88, vcc
	v_cmp_ge_u32_e32 vcc, v74, v238
	v_or_b32_e32 v74, 64, v168
	s_nop 0
	v_cndmask_b32_e32 v88, v235, v89, vcc
	v_cmp_ge_u32_e32 vcc, v74, v238
	v_max3_f32 v17, v17, v91, v88
	s_nop 0
	v_cndmask_b32_e32 v87, v235, v58, vcc
	v_or_b32_e32 v58, 0x41, v168
	v_cmp_ge_u32_e32 vcc, v58, v238
	v_or_b32_e32 v58, 0x42, v168
	s_nop 0
	v_cndmask_b32_e32 v85, v235, v59, vcc
	v_cmp_ge_u32_e32 vcc, v58, v238
	v_or_b32_e32 v58, 0x43, v168
	v_max3_f32 v17, v17, v87, v85
	v_cndmask_b32_e32 v86, v235, v60, vcc
	v_cmp_ge_u32_e32 vcc, v58, v238
	v_or_b32_e32 v58, 0x48, v168
	s_nop 0
	v_cndmask_b32_e32 v84, v235, v61, vcc
	v_cmp_ge_u32_e32 vcc, v58, v238
	v_or_b32_e32 v58, 0x49, v168
	v_max3_f32 v17, v17, v86, v84
	v_cndmask_b32_e32 v83, v235, v62, vcc
	v_cmp_ge_u32_e32 vcc, v58, v238
	v_or_b32_e32 v58, 0x4a, v168
	s_nop 0
	v_cndmask_b32_e32 v81, v235, v63, vcc
	v_cmp_ge_u32_e32 vcc, v58, v238
	v_max3_f32 v17, v17, v83, v81
	s_nop 0
	v_cndmask_b32_e32 v82, v235, v64, vcc
	v_cmp_ge_u32_e32 vcc, v169, v238
	v_cndmask_b32_e64 v64, v43, v235, s[80:81]
	v_cndmask_b32_e64 v43, v45, v235, s[86:87]
	v_cndmask_b32_e32 v80, v235, v65, vcc
	v_cmp_ge_u32_e32 vcc, v170, v238
	v_max3_f32 v17, v17, v82, v80
	v_and_b32_e32 v45, 64, v221
	v_cndmask_b32_e32 v79, v235, v66, vcc
	v_cmp_ge_u32_e32 vcc, v171, v238
	v_cndmask_b32_e64 v66, v42, v235, s[76:77]
	v_cndmask_b32_e64 v42, v46, v235, s[88:89]
	v_cndmask_b32_e32 v78, v235, v67, vcc
	v_cmp_ge_u32_e32 vcc, v172, v238
	v_max3_f32 v17, v17, v79, v78
	v_add_u32_e32 v45, 64, v45
	v_cndmask_b32_e32 v77, v235, v68, vcc
	v_cmp_ge_u32_e32 vcc, v173, v238
	s_nop 1
	v_cndmask_b32_e32 v76, v235, v69, vcc
	v_cmp_ge_u32_e32 vcc, v174, v238
	v_max3_f32 v17, v17, v77, v76
	s_nop 0
	v_cndmask_b32_e32 v75, v235, v70, vcc
	v_cmp_ge_u32_e32 vcc, v175, v238
	s_nop 1
	v_cndmask_b32_e32 v74, v235, v71, vcc
	v_cmp_ge_u32_e32 vcc, v176, v238
	v_max3_f32 v17, v17, v75, v74
	s_nop 0
	v_cndmask_b32_e32 v72, v235, v72, vcc
	v_cmp_ge_u32_e32 vcc, v177, v238
	s_nop 1
	v_cndmask_b32_e32 v71, v235, v73, vcc
	v_cmp_ge_u32_e32 vcc, v178, v238
	s_and_b64 vcc, vcc, s[8:9]
	v_max3_f32 v17, v17, v72, v71
	v_cndmask_b32_e32 v70, v235, v0, vcc
	v_cmp_ge_u32_e32 vcc, v179, v238
	s_and_b64 vcc, vcc, s[10:11]
	s_nop 0
	v_cndmask_b32_e32 v69, v235, v1, vcc
	v_cmp_ge_u32_e32 vcc, v180, v238
	s_and_b64 vcc, vcc, s[12:13]
	v_max3_f32 v0, v17, v70, v69
	v_cndmask_b32_e32 v68, v235, v2, vcc
	v_cmp_ge_u32_e32 vcc, v181, v238
	s_and_b64 vcc, vcc, s[14:15]
	v_cndmask_b32_e64 v2, v55, v235, s[46:47]
	v_cndmask_b32_e32 v65, v235, v3, vcc
	v_cmp_ge_u32_e32 vcc, v182, v238
	s_and_b64 vcc, vcc, s[16:17]
	v_max3_f32 v0, v0, v68, v65
	v_cndmask_b32_e32 v62, v235, v4, vcc
	v_cmp_ge_u32_e32 vcc, v183, v238
	s_and_b64 vcc, vcc, s[18:19]
	v_cndmask_b32_e64 v4, v54, v235, s[44:45]
	v_cndmask_b32_e32 v60, v235, v5, vcc
	v_cmp_ge_u32_e32 vcc, v184, v238
	s_and_b64 vcc, vcc, s[20:21]
	v_max3_f32 v0, v0, v62, v60
	v_cndmask_b32_e32 v61, v235, v6, vcc
	v_cmp_ge_u32_e32 vcc, v185, v238
	s_and_b64 vcc, vcc, s[22:23]
	v_cndmask_b32_e64 v5, v53, v235, s[42:43]
	v_cndmask_b32_e32 v59, v235, v7, vcc
	v_cmp_ge_u32_e32 vcc, v186, v238
	s_and_b64 vcc, vcc, s[24:25]
	v_max3_f32 v0, v0, v61, v59
	v_cndmask_b32_e32 v58, v235, v8, vcc
	v_cmp_ge_u32_e32 vcc, v187, v238
	s_and_b64 vcc, vcc, s[26:27]
	v_cndmask_b32_e64 v7, v52, v235, s[40:41]
	v_cndmask_b32_e32 v8, v235, v9, vcc
	v_cmp_ge_u32_e32 vcc, v188, v238
	s_and_b64 vcc, vcc, s[28:29]
	v_max3_f32 v0, v0, v58, v8
	v_cndmask_b32_e32 v17, v235, v10, vcc
	v_cmp_ge_u32_e32 vcc, v189, v238
	s_and_b64 vcc, vcc, s[30:31]
	v_cndmask_b32_e64 v10, v51, v235, s[38:39]
	v_cndmask_b32_e32 v9, v235, v11, vcc
	v_cmp_ge_u32_e32 vcc, v190, v238
	s_and_b64 vcc, vcc, s[34:35]
	v_max3_f32 v0, v0, v17, v9
	v_cndmask_b32_e32 v6, v235, v12, vcc
	v_cmp_ge_u32_e32 vcc, v191, v238
	s_and_b64 vcc, vcc, s[36:37]
	v_cndmask_b32_e64 v12, v50, v235, s[96:97]
	v_cndmask_b32_e32 v11, v235, v13, vcc
	v_cmp_ge_u32_e32 vcc, v192, v238
	s_and_b64 vcc, vcc, s[70:71]
	v_max3_f32 v0, v0, v6, v11
	v_cndmask_b32_e32 v63, v235, v14, vcc
	v_cmp_ge_u32_e32 vcc, v193, v238
	s_and_b64 vcc, vcc, s[2:3]
	v_cndmask_b32_e64 v14, v48, v235, s[92:93]
	v_cndmask_b32_e32 v67, v235, v15, vcc
	v_max3_f32 v0, v0, v63, v67
	v_max3_f32 v0, v0, v66, v64
	v_max3_f32 v0, v0, v44, v43
	v_cndmask_b32_e64 v15, v47, v235, s[90:91]
	v_max3_f32 v0, v0, v42, v15
	v_cndmask_b32_e64 v13, v49, v235, s[94:95]
	v_max3_f32 v0, v0, v14, v13
	v_max3_f32 v0, v0, v12, v10
	v_max3_f32 v0, v0, v7, v5
	v_max3_f32 v3, v0, v4, v2
	v_cndmask_b32_e64 v1, v56, v235, s[48:49]
	v_cndmask_b32_e64 v0, v57, v235, s[50:51]
	v_max3_f32 v46, v3, v1, v0
	v_xor_b32_e32 v3, 32, v221
	v_cmp_lt_i32_e32 vcc, v3, v45
	s_lshl_b32 s56, s56, 6
	v_cndmask_b32_e32 v3, v221, v3, vcc
	v_lshlrev_b32_e32 v3, 2, v3
	ds_bpermute_b32 v47, v3, v46
	s_ashr_i32 s57, s56, 31
	s_waitcnt lgkmcnt(0)
	v_mov_b32_e32 v45, s74
	v_mul_f32_e32 v48, 0x3fb8aa3b, v45
	v_max3_f32 v54, v46, v47, v48
	v_sub_f32_e32 v46, v222, v54
	v_exp_f32_e32 v46, v46
	v_sub_f32_e32 v47, v217, v54
	v_exp_f32_e32 v47, v47
	v_sub_f32_e32 v56, v212, v54
	v_add_f32_e32 v48, 0, v46
	v_exp_f32_e32 v73, v56
	v_add_f32_e32 v49, v47, v48
	v_sub_f32_e32 v48, v236, v54
	v_exp_f32_e32 v48, v48
	v_sub_f32_e32 v56, v210, v54
	v_exp_f32_e32 v89, v56
	v_sub_f32_e32 v56, v211, v54
	v_add_f32_e32 v50, v48, v49
	v_sub_f32_e32 v49, v237, v54
	v_exp_f32_e32 v49, v49
	v_exp_f32_e32 v210, v56
	v_sub_f32_e32 v56, v209, v54
	v_exp_f32_e32 v209, v56
	v_add_f32_e32 v51, v49, v50
	v_sub_f32_e32 v50, v216, v54
	v_exp_f32_e32 v50, v50
	v_sub_f32_e32 v56, v208, v54
	v_exp_f32_e32 v208, v56
	v_sub_f32_e32 v56, v206, v54
	v_add_f32_e32 v52, v50, v51
	v_sub_f32_e32 v51, v214, v54
	v_exp_f32_e32 v51, v51
	v_exp_f32_e32 v206, v56
	v_sub_f32_e32 v56, v207, v54
	v_exp_f32_e32 v207, v56
	v_add_f32_e32 v53, v51, v52
	v_sub_f32_e32 v52, v215, v54
	v_exp_f32_e32 v52, v52
	v_sub_f32_e32 v56, v105, v54
	v_exp_f32_e32 v105, v56
	v_sub_f32_e32 v56, v104, v54
	v_add_f32_e32 v55, v52, v53
	v_sub_f32_e32 v53, v213, v54
	v_exp_f32_e32 v53, v53
	v_exp_f32_e32 v104, v56
	v_sub_f32_e32 v56, v102, v54
	v_exp_f32_e32 v102, v56
	v_add_f32_e32 v55, v53, v55
	v_add_f32_e32 v55, v73, v55
	v_add_f32_e32 v55, v89, v55
	v_add_f32_e32 v55, v210, v55
	v_add_f32_e32 v55, v209, v55
	v_add_f32_e32 v55, v208, v55
	v_add_f32_e32 v55, v206, v55
	v_sub_f32_e32 v56, v103, v54
	v_add_f32_e32 v55, v207, v55
	v_exp_f32_e32 v103, v56
	v_sub_f32_e32 v56, v101, v54
	v_add_f32_e32 v55, v105, v55
	v_exp_f32_e32 v101, v56
	v_sub_f32_e32 v56, v100, v54
	v_add_f32_e32 v55, v104, v55
	v_exp_f32_e32 v100, v56
	v_sub_f32_e32 v56, v98, v54
	v_add_f32_e32 v55, v102, v55
	v_exp_f32_e32 v98, v56
	v_sub_f32_e32 v56, v99, v54
	v_add_f32_e32 v55, v103, v55
	v_exp_f32_e32 v99, v56
	v_sub_f32_e32 v56, v97, v54
	v_add_f32_e32 v55, v101, v55
	v_exp_f32_e32 v97, v56
	v_sub_f32_e32 v56, v96, v54
	v_add_f32_e32 v55, v100, v55
	v_exp_f32_e32 v96, v56
	v_sub_f32_e32 v56, v94, v54
	v_add_f32_e32 v55, v98, v55
	v_exp_f32_e32 v94, v56
	v_sub_f32_e32 v56, v95, v54
	v_add_f32_e32 v55, v99, v55
	v_exp_f32_e32 v95, v56
	v_sub_f32_e32 v56, v93, v54
	v_add_f32_e32 v55, v97, v55
	v_exp_f32_e32 v93, v56
	v_sub_f32_e32 v56, v92, v54
	v_add_f32_e32 v55, v96, v55
	v_exp_f32_e32 v92, v56
	v_sub_f32_e32 v56, v90, v54
	v_add_f32_e32 v55, v94, v55
	v_exp_f32_e32 v90, v56
	v_sub_f32_e32 v56, v91, v54
	v_add_f32_e32 v55, v95, v55
	v_exp_f32_e32 v91, v56
	v_sub_f32_e32 v56, v88, v54
	v_add_f32_e32 v55, v93, v55
	v_exp_f32_e32 v215, v56
	v_sub_f32_e32 v56, v87, v54
	v_add_f32_e32 v55, v92, v55
	v_exp_f32_e32 v87, v56
	v_sub_f32_e32 v56, v85, v54
	v_add_f32_e32 v55, v90, v55
	v_exp_f32_e32 v85, v56
	v_sub_f32_e32 v56, v86, v54
	v_add_f32_e32 v55, v91, v55
	v_exp_f32_e32 v86, v56
	v_sub_f32_e32 v56, v84, v54
	v_add_f32_e32 v55, v215, v55
	v_exp_f32_e32 v84, v56
	v_sub_f32_e32 v56, v83, v54
	v_add_f32_e32 v55, v87, v55
	v_exp_f32_e32 v83, v56
	v_sub_f32_e32 v56, v81, v54
	v_add_f32_e32 v55, v85, v55
	v_exp_f32_e32 v212, v56
	v_sub_f32_e32 v56, v82, v54
	v_add_f32_e32 v55, v86, v55
	v_exp_f32_e32 v216, v56
	v_sub_f32_e32 v56, v80, v54
	v_add_f32_e32 v55, v84, v55
	v_exp_f32_e32 v237, v56
	v_sub_f32_e32 v56, v79, v54
	v_add_f32_e32 v55, v83, v55
	v_exp_f32_e32 v79, v56
	v_sub_f32_e32 v56, v78, v54
	v_add_f32_e32 v55, v212, v55
	v_exp_f32_e32 v78, v56
	v_sub_f32_e32 v56, v77, v54
	v_add_f32_e32 v55, v216, v55
	v_exp_f32_e32 v77, v56
	v_sub_f32_e32 v56, v76, v54
	v_add_f32_e32 v55, v237, v55
	v_exp_f32_e32 v81, v56
	v_sub_f32_e32 v56, v75, v54
	v_add_f32_e32 v55, v79, v55
	v_exp_f32_e32 v214, v56
	v_sub_f32_e32 v56, v74, v54
	v_add_f32_e32 v55, v78, v55
	v_exp_f32_e32 v222, v56
	v_sub_f32_e32 v56, v72, v54
	v_add_f32_e32 v55, v77, v55
	v_exp_f32_e32 v238, v56
	v_sub_f32_e32 v56, v71, v54
	v_add_f32_e32 v55, v81, v55
	v_exp_f32_e32 v242, v56
	v_sub_f32_e32 v56, v70, v54
	v_add_f32_e32 v55, v214, v55
	v_exp_f32_e32 v70, v56
	v_sub_f32_e32 v56, v69, v54
	v_add_f32_e32 v55, v222, v55
	v_exp_f32_e32 v75, v56
	v_sub_f32_e32 v56, v68, v54
	v_add_f32_e32 v55, v238, v55
	v_exp_f32_e32 v82, v56
	v_sub_f32_e32 v56, v65, v54
	v_add_f32_e32 v55, v242, v55
	v_exp_f32_e32 v211, v56
	v_sub_f32_e32 v56, v62, v54
	v_add_f32_e32 v55, v70, v55
	v_exp_f32_e32 v236, v56
	v_sub_f32_e32 v56, v60, v54
	v_add_f32_e32 v55, v75, v55
	v_exp_f32_e32 v239, v56
	v_sub_f32_e32 v56, v61, v54
	v_add_f32_e32 v55, v82, v55
	v_exp_f32_e32 v244, v56
	v_sub_f32_e32 v56, v59, v54
	v_add_f32_e32 v55, v211, v55
	v_exp_f32_e32 v246, v56
	v_sub_f32_e32 v56, v58, v54
	v_add_f32_e32 v55, v236, v55
	v_exp_f32_e32 v76, v56
	v_sub_f32_e32 v8, v8, v54
	v_add_f32_e32 v55, v239, v55
	v_exp_f32_e32 v88, v8
	v_sub_f32_e32 v17, v17, v54
	v_add_f32_e32 v55, v244, v55
	v_exp_f32_e32 v213, v17
	v_sub_f32_e32 v9, v9, v54
	v_add_f32_e32 v55, v246, v55
	v_exp_f32_e32 v217, v9
	v_sub_f32_e32 v6, v6, v54
	v_add_f32_e32 v55, v76, v55
	v_exp_f32_e32 v240, v6
	v_add_f32_e32 v8, v88, v55
	v_add_f32_e32 v8, v213, v8
	v_add_f32_e32 v8, v217, v8
	v_add_f32_e32 v6, v240, v8
	v_sub_f32_e32 v8, v11, v54
	v_exp_f32_e32 v241, v8
	v_sub_f32_e32 v8, v63, v54
	v_exp_f32_e32 v243, v8
	v_sub_f32_e32 v8, v67, v54
	v_exp_f32_e32 v245, v8
	v_sub_f32_e32 v8, v66, v54
	v_exp_f32_e32 v66, v8
	v_sub_f32_e32 v8, v64, v54
	v_add_f32_e32 v6, v241, v6
	v_exp_f32_e32 v67, v8
	v_sub_f32_e32 v8, v44, v54
	v_add_f32_e32 v6, v243, v6
	v_exp_f32_e32 v68, v8
	v_sub_f32_e32 v8, v43, v54
	v_add_f32_e32 v6, v245, v6
	v_exp_f32_e32 v69, v8
	v_sub_f32_e32 v8, v42, v54
	v_add_f32_e32 v6, v66, v6
	v_exp_f32_e32 v71, v8
	v_sub_f32_e32 v8, v15, v54
	v_add_f32_e32 v6, v67, v6
	v_exp_f32_e32 v72, v8
	v_sub_f32_e32 v8, v14, v54
	v_add_f32_e32 v6, v68, v6
	v_exp_f32_e32 v74, v8
	v_sub_f32_e32 v8, v13, v54
	v_add_f32_e32 v6, v69, v6
	v_exp_f32_e32 v80, v8
	v_sub_f32_e32 v8, v12, v54
	v_add_f32_e32 v6, v71, v6
	v_exp_f32_e32 v58, v8
	v_sub_f32_e32 v8, v10, v54
	v_add_f32_e32 v6, v72, v6
	v_exp_f32_e32 v59, v8
	v_sub_f32_e32 v7, v7, v54
	v_add_f32_e32 v6, v74, v6
	v_exp_f32_e32 v60, v7
	v_sub_f32_e32 v5, v5, v54
	v_add_f32_e32 v6, v80, v6
	v_exp_f32_e32 v61, v5
	v_sub_f32_e32 v4, v4, v54
	v_add_f32_e32 v6, v58, v6
	v_exp_f32_e32 v62, v4
	v_sub_f32_e32 v2, v2, v54
	v_add_f32_e32 v6, v59, v6
	v_exp_f32_e32 v63, v2
	v_sub_f32_e32 v1, v1, v54
	v_add_f32_e32 v6, v60, v6
	v_exp_f32_e32 v64, v1
	v_sub_f32_e32 v0, v0, v54
	v_add_f32_e32 v5, v61, v6
	v_exp_f32_e32 v65, v0
	v_add_f32_e32 v4, v62, v5
	v_add_f32_e32 v2, v63, v4
	v_add_f32_e32 v1, v64, v2
	v_add_f32_e32 v0, v65, v1
	ds_bpermute_b32 v1, v3, v0
	s_waitcnt lgkmcnt(0)
	v_add_f32_e32 v0, v0, v1
	v_fma_f32 v1, v45, s54, -v54
	v_exp_f32_e32 v1, v1
	s_nop 0
	v_add_f32_e32 v17, v1, v0
	v_cvt_pk_bf16_f32 v0, v46, v47
	v_cvt_pk_bf16_f32 v1, v48, v49
	v_cvt_pk_bf16_f32 v2, v50, v51
	v_cvt_pk_bf16_f32 v3, v52, v53
	ds_read_b64_tr_b16 v[4:5], v194 offset:61440
	ds_read_b64_tr_b16 v[6:7], v194 offset:62976
	s_waitcnt lgkmcnt(0)
	v_mfma_f32_32x32x16_bf16 v[42:57], v[4:7], v[0:3], 0
	ds_read_b64_tr_b16 v[4:5], v194 offset:61504
	ds_read_b64_tr_b16 v[6:7], v194 offset:63040
	v_cvt_pk_bf16_f32 v224, v73, v89
	v_cvt_pk_bf16_f32 v225, v210, v209
	v_cvt_pk_bf16_f32 v226, v208, v206
	v_cvt_pk_bf16_f32 v227, v207, v105
	ds_read_b64_tr_b16 v[206:207], v194 offset:64512
	ds_read_b64_tr_b16 v[208:209], v195 offset:4608
	v_rcp_f32_e32 v17, v17
	s_waitcnt lgkmcnt(2)
	v_mfma_f32_32x32x16_bf16 v[0:15], v[4:7], v[0:3], 0
	s_waitcnt lgkmcnt(0)
	v_mfma_f32_32x32x16_bf16 v[42:57], v[206:209], v[224:227], v[42:57]
	ds_read_b64_tr_b16 v[206:207], v194 offset:64576
	ds_read_b64_tr_b16 v[208:209], v195 offset:4672
	v_cvt_pk_bf16_f32 v102, v104, v102
	v_cvt_pk_bf16_f32 v103, v103, v101
	v_cvt_pk_bf16_f32 v104, v100, v98
	v_cvt_pk_bf16_f32 v105, v99, v97
	ds_read_b64_tr_b16 v[98:99], v195 offset:6144
	ds_read_b64_tr_b16 v[100:101], v195 offset:7680
	s_waitcnt lgkmcnt(2)
	v_mfma_f32_32x32x16_bf16 v[0:15], v[206:209], v[224:227], v[0:15]
	s_waitcnt lgkmcnt(0)
	v_mfma_f32_32x32x16_bf16 v[42:57], v[98:101], v[102:105], v[42:57]
	ds_read_b64_tr_b16 v[98:99], v195 offset:6208
	ds_read_b64_tr_b16 v[100:101], v195 offset:7744
	v_cvt_pk_bf16_f32 v94, v96, v94
	v_cvt_pk_bf16_f32 v95, v95, v93
	v_cvt_pk_bf16_f32 v96, v92, v90
	v_cvt_pk_bf16_f32 v97, v91, v215
	ds_read_b64_tr_b16 v[90:91], v195 offset:9216
	ds_read_b64_tr_b16 v[92:93], v195 offset:10752
	s_waitcnt lgkmcnt(2)
	v_mfma_f32_32x32x16_bf16 v[0:15], v[98:101], v[102:105], v[0:15]
	s_waitcnt lgkmcnt(0)
	v_mfma_f32_32x32x16_bf16 v[42:57], v[90:93], v[94:97], v[42:57]
	ds_read_b64_tr_b16 v[90:91], v195 offset:9280
	ds_read_b64_tr_b16 v[92:93], v195 offset:10816
	s_waitcnt lgkmcnt(0)
	v_mfma_f32_32x32x16_bf16 v[0:15], v[90:93], v[94:97], v[0:15]
	v_cvt_pk_bf16_f32 v90, v87, v85
	v_cvt_pk_bf16_f32 v91, v86, v84
	v_cvt_pk_bf16_f32 v92, v83, v212
	v_cvt_pk_bf16_f32 v93, v216, v237
	ds_read_b64_tr_b16 v[84:85], v195 offset:12288
	ds_read_b64_tr_b16 v[86:87], v195 offset:13824
	s_waitcnt lgkmcnt(0)
	v_mfma_f32_32x32x16_bf16 v[42:57], v[84:87], v[90:93], v[42:57]
	ds_read_b64_tr_b16 v[84:85], v195 offset:12352
	ds_read_b64_tr_b16 v[86:87], v195 offset:13888
	s_waitcnt lgkmcnt(0)
	v_mfma_f32_32x32x16_bf16 v[0:15], v[84:87], v[90:93], v[0:15]
	v_cvt_pk_bf16_f32 v84, v79, v78
	v_cvt_pk_bf16_f32 v85, v77, v81
	v_cvt_pk_bf16_f32 v86, v214, v222
	v_cvt_pk_bf16_f32 v87, v238, v242
	ds_read_b64_tr_b16 v[90:91], v195 offset:15360
	ds_read_b64_tr_b16 v[92:93], v195 offset:16896
	s_waitcnt lgkmcnt(0)
	v_mfma_f32_32x32x16_bf16 v[42:57], v[90:93], v[84:87], v[42:57]
	ds_read_b64_tr_b16 v[90:91], v195 offset:15424
	ds_read_b64_tr_b16 v[92:93], v195 offset:16960
	s_waitcnt lgkmcnt(0)
	v_mfma_f32_32x32x16_bf16 v[0:15], v[90:93], v[84:87], v[0:15]
	v_cvt_pk_bf16_f32 v84, v70, v75
	v_cvt_pk_bf16_f32 v85, v82, v211
	v_cvt_pk_bf16_f32 v86, v236, v239
	v_cvt_pk_bf16_f32 v87, v244, v246
	ds_read_b64_tr_b16 v[90:91], v195 offset:18432
	ds_read_b64_tr_b16 v[92:93], v195 offset:19968
	s_waitcnt lgkmcnt(0)
	v_mfma_f32_32x32x16_bf16 v[42:57], v[90:93], v[84:87], v[42:57]
	ds_read_b64_tr_b16 v[90:91], v195 offset:18496
	ds_read_b64_tr_b16 v[92:93], v195 offset:20032
	v_cvt_pk_bf16_f32 v76, v76, v88
	v_cvt_pk_bf16_f32 v77, v213, v217
	v_cvt_pk_bf16_f32 v78, v240, v241
	v_cvt_pk_bf16_f32 v79, v243, v245
	s_waitcnt lgkmcnt(0)
	v_mfma_f32_32x32x16_bf16 v[0:15], v[90:93], v[84:87], v[0:15]
	ds_read_b64_tr_b16 v[82:83], v195 offset:21504
	ds_read_b64_tr_b16 v[84:85], v195 offset:23040
	s_waitcnt lgkmcnt(0)
	v_mfma_f32_32x32x16_bf16 v[42:57], v[82:85], v[76:79], v[42:57]
	ds_read_b64_tr_b16 v[82:83], v195 offset:21568
	ds_read_b64_tr_b16 v[84:85], v195 offset:23104
	v_cvt_pk_bf16_f32 v66, v66, v67
	v_cvt_pk_bf16_f32 v67, v68, v69
	v_cvt_pk_bf16_f32 v68, v71, v72
	v_cvt_pk_bf16_f32 v69, v74, v80
	ds_read_b64_tr_b16 v[70:71], v195 offset:24576
	ds_read_b64_tr_b16 v[72:73], v195 offset:26112
	s_waitcnt lgkmcnt(0)
	v_mfma_f32_32x32x16_bf16 v[42:57], v[70:73], v[66:69], v[42:57]
	ds_read_b64_tr_b16 v[70:71], v195 offset:24640
	ds_read_b64_tr_b16 v[72:73], v195 offset:26176
	v_cvt_pk_bf16_f32 v58, v58, v59
	v_cvt_pk_bf16_f32 v59, v60, v61
	v_cvt_pk_bf16_f32 v60, v62, v63
	v_cvt_pk_bf16_f32 v61, v64, v65
	ds_read_b64_tr_b16 v[62:63], v195 offset:27648
	ds_read_b64_tr_b16 v[64:65], v195 offset:29184
	v_mfma_f32_32x32x16_bf16 v[0:15], v[82:85], v[76:79], v[0:15]
	s_waitcnt lgkmcnt(0)
	v_mfma_f32_32x32x16_bf16 v[42:57], v[62:65], v[58:61], v[42:57]
	ds_read_b64_tr_b16 v[62:63], v195 offset:27712
	ds_read_b64_tr_b16 v[64:65], v195 offset:29248
	v_mfma_f32_32x32x16_bf16 v[0:15], v[70:73], v[66:69], v[0:15]
	s_nop 8
	v_mul_f32_e32 v42, v42, v17
	v_mul_f32_e32 v43, v43, v17
	v_cvt_pk_bf16_f32 v42, v42, v43
	v_mul_f32_e32 v43, v44, v17
	v_mul_f32_e32 v44, v45, v17
	v_cvt_pk_bf16_f32 v43, v43, v44
	v_add_u32_e32 v44, v157, v126
	s_waitcnt lgkmcnt(0)
	v_mfma_f32_32x32x16_bf16 v[0:15], v[62:65], v[58:61], v[0:15]
	ds_write_b64 v44, v[42:43]
	v_mul_f32_e32 v42, v46, v17
	v_mul_f32_e32 v43, v47, v17
	v_cvt_pk_bf16_f32 v42, v42, v43
	v_mul_f32_e32 v43, v48, v17
	v_mul_f32_e32 v44, v49, v17
	v_cvt_pk_bf16_f32 v43, v43, v44
	v_add_u32_e32 v44, v157, v158
	ds_write_b64 v44, v[42:43]
	v_mul_f32_e32 v42, v50, v17
	v_mul_f32_e32 v43, v51, v17
	v_cvt_pk_bf16_f32 v42, v42, v43
	v_mul_f32_e32 v43, v52, v17
	v_mul_f32_e32 v44, v53, v17
	v_cvt_pk_bf16_f32 v43, v43, v44
	v_add_u32_e32 v44, v157, v159
	ds_write_b64 v44, v[42:43]
	v_mul_f32_e32 v42, v54, v17
	v_mul_f32_e32 v43, v55, v17
	v_cvt_pk_bf16_f32 v42, v42, v43
	v_mul_f32_e32 v43, v56, v17
	v_mul_f32_e32 v44, v57, v17
	v_cvt_pk_bf16_f32 v43, v43, v44
	v_add_u32_e32 v44, v157, v160
	v_mul_f32_e32 v0, v0, v17
	v_mul_f32_e32 v1, v1, v17
	ds_write_b64 v44, v[42:43]
	v_cvt_pk_bf16_f32 v0, v0, v1
	v_mul_f32_e32 v1, v2, v17
	v_mul_f32_e32 v2, v3, v17
	v_cvt_pk_bf16_f32 v1, v1, v2
	v_add_u32_e32 v2, v157, v161
	ds_write_b64 v2, v[0:1]
	v_mul_f32_e32 v0, v4, v17
	v_mul_f32_e32 v1, v5, v17
	v_cvt_pk_bf16_f32 v0, v0, v1
	v_mul_f32_e32 v1, v6, v17
	v_mul_f32_e32 v2, v7, v17
	v_cvt_pk_bf16_f32 v1, v1, v2
	v_add_u32_e32 v2, v157, v162
	ds_write_b64 v2, v[0:1]
	v_mul_f32_e32 v0, v8, v17
	v_mul_f32_e32 v1, v9, v17
	v_cvt_pk_bf16_f32 v0, v0, v1
	v_mul_f32_e32 v1, v10, v17
	v_mul_f32_e32 v2, v11, v17
	v_cvt_pk_bf16_f32 v1, v1, v2
	v_add_u32_e32 v2, v157, v163
	ds_write_b64 v2, v[0:1]
	v_mul_f32_e32 v0, v12, v17
	v_mul_f32_e32 v1, v13, v17
	v_cvt_pk_bf16_f32 v0, v0, v1
	v_mul_f32_e32 v1, v14, v17
	v_mul_f32_e32 v2, v15, v17
	v_cvt_pk_bf16_f32 v1, v1, v2
	v_add_u32_e32 v2, v157, v164
	ds_write_b64 v2, v[0:1]
	v_mov_b32_e32 v1, s7
	v_or_b32_e32 v0, s6, v134
	v_lshl_add_u64 v[4:5], s[56:57], 1, v[136:137]
	v_lshlrev_b64 v[0:1], 11, v[0:1]
	s_waitcnt lgkmcnt(0)
	v_lshl_add_u64 v[6:7], v[4:5], 0, v[0:1]
	v_add_u32_e32 v0, v165, v166
	ds_read_b128 v[0:3], v0
	s_waitcnt lgkmcnt(0)
	global_store_dwordx4 v[6:7], v[0:3], off
	s_nop 1
	v_mov_b32_e32 v1, s7
	v_or_b32_e32 v0, s6, v138
	v_lshlrev_b64 v[0:1], 11, v[0:1]
	v_lshl_add_u64 v[6:7], v[4:5], 0, v[0:1]
	ds_read_b128 v[0:3], v203
	s_waitcnt lgkmcnt(0)
	global_store_dwordx4 v[6:7], v[0:3], off
	s_nop 1
	v_mov_b32_e32 v1, s7
	v_or_b32_e32 v0, s6, v140
	v_lshlrev_b64 v[0:1], 11, v[0:1]
	v_lshl_add_u64 v[6:7], v[4:5], 0, v[0:1]
	ds_read_b128 v[0:3], v204
	s_waitcnt lgkmcnt(0)
	global_store_dwordx4 v[6:7], v[0:3], off
	s_nop 1
	v_mov_b32_e32 v1, s7
	v_or_b32_e32 v0, s6, v142
	v_lshlrev_b64 v[0:1], 11, v[0:1]
	v_lshl_add_u64 v[4:5], v[4:5], 0, v[0:1]
	ds_read_b128 v[0:3], v205
	s_waitcnt lgkmcnt(0)
	global_store_dwordx4 v[4:5], v[0:3], off
	s_branch .LBB0_1216
